# v118 + G5 tile-seam side-buffer stores write-through (sc1)
# baseline (speedup 1.0000x reference)
.LBB0_1261:
	v_mbcnt_lo_u32_b32 v137, -1, 0
	v_mbcnt_hi_u32_b32 v137, -1, v137
	s_waitcnt vmcnt(0)
	v_mov_b32_e32 v139, v10
	v_ashrrev_i32_e32 v138, 4, v137
	v_and_b32_e32 v183, 15, v137
	v_lshl_add_u32 v144, v138, 3, s66
	v_lshlrev_b32_e32 v137, 6, v138
	v_lshlrev_b32_e32 v138, 2, v183
	v_add3_u32 v137, s74, v137, v138
	v_mov_b32_e32 v138, v9
	v_mov_b32_e32 v9, v11
	v_pk_add_f32 v[8:9], v[138:139], v[8:9]
	ds_write_b32 v137, v136 offset:4096
	v_add_f32_e32 v8, v8, v9
	v_fmamk_f32 v8, v8, 0x3a800000, v206
	v_rsq_f32_e32 v8, v8
	v_or_b32_e32 v9, v183, v191
	v_lshlrev_b32_e32 v10, 2, v9
	v_mov_b32_e32 v9, v6
	ds_bpermute_b32 v156, v10, v8
	ds_bpermute_b32 v196, v10, v8 offset:64
	ds_bpermute_b32 v192, v10, v8 offset:128
	ds_bpermute_b32 v188, v10, v8 offset:192
	v_mov_b32_e32 v8, v5
	v_mov_b32_e32 v5, v7
	v_pk_add_f32 v[4:5], v[8:9], v[4:5]
	v_lshl_add_u32 v184, s4, 7, v144
	v_add_f32_e32 v4, v4, v5
	v_fmamk_f32 v4, v4, 0x3a800000, v206
	v_rsq_f32_e32 v4, v4
	s_nop 0
	ds_bpermute_b32 v182, v10, v4 offset:192
	ds_bpermute_b32 v194, v10, v4
	ds_bpermute_b32 v190, v10, v4 offset:64
	ds_bpermute_b32 v186, v10, v4 offset:128
	s_waitcnt lgkmcnt(4)
	v_pk_mul_f32 v[138:139], v[42:43], v[188:189] op_sel_hi:[1,0]
	v_pk_mul_f32 v[136:137], v[40:41], v[188:189] op_sel_hi:[1,0]
	v_pk_mul_f32 v[142:143], v[38:39], v[188:189] op_sel_hi:[1,0]
	v_pk_mul_f32 v[140:141], v[36:37], v[188:189] op_sel_hi:[1,0]
	s_waitcnt lgkmcnt(3)
	v_pk_mul_f32 v[8:9], v[20:21], v[182:183] op_sel_hi:[1,0]
	v_cndmask_b32_e64 v20, 0, 1, s[12:13]
	v_pk_mul_f32 v[6:7], v[26:27], v[182:183] op_sel_hi:[1,0]
	v_pk_mul_f32 v[4:5], v[24:25], v[182:183] op_sel_hi:[1,0]
	v_pk_mul_f32 v[10:11], v[22:23], v[182:183] op_sel_hi:[1,0]
	v_cmp_lt_u32_e32 vcc, 13, v183
	v_lshlrev_b32_e32 v209, 2, v144
	v_cmp_ne_u32_e64 s[4:5], 1, v20
	s_and_saveexec_b64 s[56:57], vcc
	s_cbranch_execz .LBB0_1264
	v_add_lshl_u32 v20, s71, v183, 9
	v_add3_u32 v21, s72, v20, v209
	v_add3_u32 v20, s80, v20, v209
	s_and_b64 vcc, exec, s[4:5]
	ds_write_b128 v21, v[136:139]
	ds_write_b128 v21, v[140:143] offset:16
	ds_write_b128 v20, v[4:7]
	ds_write_b128 v21, v[8:11] offset:2064
	s_cbranch_vccnz .LBB0_1264
	s_ashr_i32 s55, s54, 31
	v_add_u32_e32 v176, -14, v183
	v_lshl_add_u64 v[20:21], s[54:55], 1, v[176:177]
	v_mov_b64_e32 v[22:23], s[22:23]
	v_mad_u64_u32 v[22:23], s[58:59], v20, s81, v[22:23]
	v_mad_i32_i24 v23, v21, s81, v23
	v_ashrrev_i32_e32 v185, 31, v184
	v_lshl_add_u64 v[20:21], v[184:185], 2, v[22:23]
	global_store_dwordx4 v[20:21], v[4:7], off sc1
	global_store_dwordx4 v[20:21], v[8:11], off offset:16 sc1

.LBB0_1266:
	s_andn2_saveexec_b64 s[56:57], s[56:57]
	s_cbranch_execz .LBB0_1268
	v_lshl_or_b32 v166, s54, 1, v183
	v_mov_b64_e32 v[160:161], s[26:27]
	v_mov_b64_e32 v[164:165], s[24:25]
	s_ashr_i32 s37, s54, 31
	v_mad_u64_u32 v[160:161], s[54:55], v166, s81, v[160:161]
	v_ashrrev_i32_e32 v185, 31, v184
	v_mad_u64_u32 v[164:165], s[54:55], v166, s81, v[164:165]
	v_mad_i32_i24 v161, s37, v208, v161
	v_lshlrev_b64 v[162:163], 2, v[184:185]
	v_mad_i32_i24 v165, s37, v208, v165
	v_lshl_add_u64 v[160:161], v[160:161], 0, v[162:163]
	v_lshl_add_u64 v[162:163], v[164:165], 0, v[162:163]
	global_store_dwordx4 v[162:163], v[144:147], off sc1
	global_store_dwordx4 v[160:161], v[152:155], off sc1
	global_store_dwordx4 v[162:163], v[148:151], off offset:16 sc1
	global_store_dwordx4 v[160:161], v[156:159], off offset:16 sc1
